# own: waves 4-7 take query sub-blocks 6,7,4,5 so each SIMD pair gets 5 causal sub-tiles
# speedup vs baseline: 1.0162x; 1.0032x over previous
.LBB0_275:
	s_or_b64 exec, exec, s[0:1]
	s_and_b64 vcc, exec, s[82:83]
	s_barrier
	s_cbranch_vccnz .LBB0_298
	s_waitcnt vmcnt(3)
	v_lshlrev_b32_e32 v1, 3, v188
	v_and_b32_e32 v0, 56, v1
	s_waitcnt vmcnt(0)
	v_and_b32_e32 v4, 0xf8, v1
	v_mul_u32_u24_e32 v1, 0x90, v194
	v_lshlrev_b32_e32 v3, 1, v0
	v_add3_u32 v175, 0, v1, v3
	v_mul_u32_u24_e32 v1, 0x90, v123
	v_add3_u32 v123, 0, v1, v3
	v_mul_u32_u24_e32 v1, 0x90, v182
	v_add3_u32 v176, 0, v1, v3
	v_mul_u32_u24_e32 v1, 0x90, v183
	v_add3_u32 v177, 0, v1, v3
	v_mul_u32_u24_e32 v1, 0x210, v197
	v_lshlrev_b32_e32 v3, 1, v4
	v_add3_u32 v182, 0, v1, v3
	v_mul_u32_u24_e32 v1, 0x210, v109
	v_add3_u32 v183, 0, v1, v3
	v_mul_u32_u24_e32 v1, 0x210, v111
	v_mov_b32_e32 v121, 0
	v_add3_u32 v185, 0, v1, v3
	v_mul_u32_u24_e32 v1, 0x210, v113
	v_and_b32_e32 v252, 4, v196
	v_lshrrev_b32_e32 v252, 1, v252
	v_xor_b32_e32 v252, v196, v252
	v_lshlrev_b32_e32 v174, 5, v252
	v_add3_u32 v186, 0, v1, v3
	v_mul_u32_u24_e32 v1, 0x90, v146
	v_mul_u32_u24_e32 v3, 0x210, v146
	v_mov_b32_e32 v125, v121
	v_lshlrev_b32_e32 v5, 7, v146
	v_lshlrev_b32_e32 v2, 12, v197
	v_lshlrev_b32_e32 v6, 12, v109
	v_lshlrev_b32_e32 v8, 12, v111
	v_lshlrev_b32_e32 v10, 12, v113
	v_or_b32_e32 v48, v174, v146
	v_lshl_add_u64 v[12:13], s[64:65], 0, v[124:125]
	v_lshl_or_b32 v14, v252, 12, v5
	v_mov_b32_e32 v15, v121
	v_add3_u32 v187, v1, v124, 0
	v_add3_u32 v1, v3, v120, 0
	s_mov_b32 s13, 0
	v_cmp_eq_u32_e64 s[8:9], 0, v184
	v_cmp_gt_u32_e64 s[10:11], 2, v181
	v_or_b32_e32 v184, 31, v174
	v_or_b32_e32 v49, 16, v48
	v_lshl_add_u64 v[50:51], v[12:13], 0, v[14:15]
	v_lshl_add_u64 v[52:53], s[50:51], 0, v[120:121]
	v_mov_b32_e32 v54, v48
	v_mov_b32_e32 v55, v48
	v_add_u32_e32 v197, 0x9000, v1
	v_lshlrev_b32_e32 v56, 1, v112
	v_lshlrev_b32_e32 v58, 1, v0
	v_lshlrev_b32_e32 v60, 1, v108
	v_lshlrev_b32_e32 v62, 1, v110
	v_lshlrev_b32_e32 v120, 1, v114
	v_lshlrev_b32_e32 v64, 1, v2
	v_lshlrev_b32_e32 v66, 1, v4
	v_lshlrev_b32_e32 v68, 1, v6
	v_lshlrev_b32_e32 v70, 1, v8
	v_lshlrev_b32_e32 v72, 1, v10
	s_movk_i32 s4, 0x180
	s_mov_b32 s5, 0xf149f2ca
	s_mov_b32 s22, 0xefa18f08
	v_lshlrev_b32_e32 v74, 1, v122
	v_mov_b32_e32 v57, v121
	v_mov_b32_e32 v59, v121
	v_mov_b32_e32 v61, v121
	v_mov_b32_e32 v63, v121
	v_mov_b32_e32 v198, 0xf149f2ca
	s_mov_b32 s23, s2
	s_branch .LBB0_278
